# attention tile: exp2 argument via one fma per score (m*log2e hoisted) instead of subtract+multiply
# speedup vs baseline: 1.0623x; 1.0110x over previous
.LBB0_236:
	v_mul_f32_e32 v250, 0x3fb8aa3b, v147
	v_mov_b32_e32 v251, 0x3fb8aa3b
	v_fma_f32 v32, v32, v251, -v250
	v_exp_f32_e32 v80, v32
	v_fma_f32 v32, v49, v251, -v250
	v_fma_f32 v34, v34, v251, -v250
	v_fma_f32 v48, v48, v251, -v250
	v_exp_f32_e32 v66, v32
	v_fma_f32 v32, v33, v251, -v250
	v_fma_f32 v33, v50, v251, -v250
	v_exp_f32_e32 v81, v34
	v_fma_f32 v34, v51, v251, -v250
	v_fma_f32 v36, v36, v251, -v250
	v_exp_f32_e32 v65, v48
	v_exp_f32_e32 v33, v33
	v_exp_f32_e32 v48, v34
	v_fma_f32 v34, v35, v251, -v250
	v_fma_f32 v35, v52, v251, -v250
	v_exp_f32_e32 v82, v36
	v_fma_f32 v36, v53, v251, -v250
	v_exp_f32_e32 v35, v35
	v_exp_f32_e32 v50, v36
	v_fma_f32 v38, v38, v251, -v250
	v_add_f32_e32 v49, v33, v81
	v_fma_f32 v36, v37, v251, -v250
	v_fma_f32 v37, v54, v251, -v250
	v_exp_f32_e32 v83, v38
	v_fma_f32 v38, v55, v251, -v250
	v_cvt_pk_bf16_f32 v69, v33, v48
	v_lshlrev_b32_e32 v33, 1, v132
	v_add3_u32 v33, s36, v162, v33
	v_add_f32_e32 v51, v35, v82
	v_exp_f32_e32 v37, v37
	v_exp_f32_e32 v52, v38
	v_cvt_pk_bf16_f32 v70, v35, v50
	v_add_u32_e32 v35, 0x2000, v33
	ds_read2_b64 v[72:75], v35 offset1:2
	ds_read2_b64 v[76:79], v35 offset0:4 offset1:6
	v_cvt_pk_bf16_f32 v68, v65, v66
	v_cvt_pk_bf16_f32 v71, v37, v52
	v_add_u32_e32 v33, 0x3000, v33
	v_fma_f32 v40, v40, v251, -v250
	s_waitcnt lgkmcnt(1)
	v_mfma_f32_32x32x16_bf16 v[0:15], v[72:75], v[68:71], v[0:15]
	ds_read2_b64 v[72:75], v33 offset0:64 offset1:66
	v_fma_f32 v42, v42, v251, -v250
	v_fma_f32 v44, v44, v251, -v250
	v_exp_f32_e32 v84, v40
	v_fma_f32 v40, v57, v251, -v250
	v_exp_f32_e32 v85, v42
	v_fma_f32 v42, v59, v251, -v250
	v_exp_f32_e32 v86, v44
	v_fma_f32 v44, v61, v251, -v250
	v_fma_f32 v46, v46, v251, -v250
	s_waitcnt lgkmcnt(0)
	v_mfma_f32_32x32x16_bf16 v[16:31], v[72:75], v[68:71], v[16:31]
	ds_read2_b64 v[72:75], v33 offset0:68 offset1:70
	v_fma_f32 v38, v39, v251, -v250
	v_fma_f32 v39, v56, v251, -v250
	v_exp_f32_e32 v54, v40
	v_fma_f32 v40, v41, v251, -v250
	v_fma_f32 v41, v58, v251, -v250
	v_exp_f32_e32 v56, v42
	v_fma_f32 v42, v43, v251, -v250
	v_fma_f32 v43, v60, v251, -v250
	v_exp_f32_e32 v58, v44
	v_fma_f32 v44, v45, v251, -v250
	v_fma_f32 v45, v62, v251, -v250
	v_exp_f32_e32 v62, v46
	v_fma_f32 v46, v63, v251, -v250
	v_exp_f32_e32 v39, v39
	v_exp_f32_e32 v41, v41
	v_exp_f32_e32 v43, v43
	v_exp_f32_e32 v45, v45
	v_exp_f32_e32 v60, v46
	v_cvt_pk_bf16_f32 v68, v39, v54
	v_cvt_pk_bf16_f32 v69, v41, v56
	v_cvt_pk_bf16_f32 v70, v43, v58
	v_cvt_pk_bf16_f32 v71, v45, v60
	s_waitcnt lgkmcnt(0)
	s_nop 0
	v_mfma_f32_32x32x16_bf16 v[16:31], v[72:75], v[68:71], v[16:31]
	ds_read2_b64 v[72:75], v35 offset0:8 offset1:10
	v_exp_f32_e32 v32, v32
	v_exp_f32_e32 v34, v34
	v_exp_f32_e32 v36, v36
	v_exp_f32_e32 v38, v38
	v_mfma_f32_32x32x16_bf16 v[0:15], v[76:79], v[68:71], v[0:15]
	v_cvt_pk_bf16_f32 v68, v80, v32
	v_cvt_pk_bf16_f32 v69, v81, v34
	v_cvt_pk_bf16_f32 v70, v82, v36
	v_cvt_pk_bf16_f32 v71, v83, v38
	v_fma_f32 v46, v47, v251, -v250
	s_waitcnt lgkmcnt(0)
	v_mfma_f32_32x32x16_bf16 v[0:15], v[72:75], v[68:71], v[0:15]
	ds_read2_b64 v[72:75], v33 offset0:72 offset1:74
	v_exp_f32_e32 v40, v40
	v_exp_f32_e32 v42, v42
	v_exp_f32_e32 v44, v44
	v_exp_f32_e32 v46, v46
	s_waitcnt lgkmcnt(0)
	v_mfma_f32_32x32x16_bf16 v[16:31], v[72:75], v[68:71], v[16:31]
	ds_read2_b64 v[72:75], v35 offset0:12 offset1:14
	v_cvt_pk_bf16_f32 v68, v84, v40
	v_cvt_pk_bf16_f32 v69, v85, v42
	v_cvt_pk_bf16_f32 v70, v86, v44
	v_cvt_pk_bf16_f32 v71, v62, v46
	v_add_f32_e32 v67, v65, v80
	v_add_f32_e32 v53, v37, v83
	s_waitcnt lgkmcnt(0)
	v_mfma_f32_32x32x16_bf16 v[0:15], v[72:75], v[68:71], v[0:15]
	ds_read2_b64 v[72:75], v33 offset0:76 offset1:78
	v_mov_b32_e32 v33, v153
	v_add_f32_e64 v32, v66, v32
	v_add_f32_e64 v33, v67, v33
	v_add_f32_e32 v55, v39, v84
	v_pk_add_f32 v[32:33], v[32:33], v[32:33] op_sel_hi:[0,1]
	v_mov_b32_e32 v35, v33
	v_pk_add_f32 v[32:33], v[48:49], v[34:35]
	v_add_f32_e32 v57, v41, v85
	v_pk_add_f32 v[32:33], v[32:33], v[32:33] op_sel_hi:[0,1]
	v_mov_b32_e32 v37, v33
	v_pk_add_f32 v[32:33], v[50:51], v[36:37]
	v_add_f32_e32 v59, v43, v86
	v_pk_add_f32 v[32:33], v[32:33], v[32:33] op_sel_hi:[0,1]
	v_mov_b32_e32 v39, v33
	v_pk_add_f32 v[32:33], v[52:53], v[38:39]
	v_add_f32_e32 v61, v45, v62
	v_pk_add_f32 v[32:33], v[32:33], v[32:33] op_sel_hi:[0,1]
	v_mov_b32_e32 v41, v33
	v_pk_add_f32 v[32:33], v[54:55], v[40:41]
	s_waitcnt lgkmcnt(0)
	v_mfma_f32_32x32x16_bf16 v[16:31], v[72:75], v[68:71], v[16:31]
	v_pk_add_f32 v[32:33], v[32:33], v[32:33] op_sel_hi:[0,1]
	v_mov_b32_e32 v43, v33
	v_pk_add_f32 v[32:33], v[56:57], v[42:43]
	s_nop 0
	v_pk_add_f32 v[32:33], v[32:33], v[32:33] op_sel_hi:[0,1]
	v_mov_b32_e32 v45, v33
	v_pk_add_f32 v[32:33], v[58:59], v[44:45]
	s_nop 0
	v_pk_add_f32 v[32:33], v[32:33], v[32:33] op_sel_hi:[0,1]
	v_mov_b32_e32 v47, v33
	v_pk_add_f32 v[32:33], v[60:61], v[46:47]
	s_nop 0
	v_add_f32_e32 v32, v32, v33
	v_fmac_f32_e32 v32, v144, v64
	v_mov_b32_e32 v144, v32
